# scan: chunk loop unrolled by two with a second raw q/k/v register set, global rows prefetched two chunks further ahead
# speedup vs baseline: 1.0134x; 1.0034x over previous
; #define LAS __attribute__((address_space(3)))
; #define SC_LOAD(c_) do { const bf16* rp_ = proj + (size_t)scan_row16(b, dir, (c_), st) * HIN + h * 128 + sc8 * 8; \
;         rq = *(const u32x4*)rp_; rk = *(const u32x4*)(rp_ + kcol - h * 128); rv = *(const u32x4*)(rp_ + 3072); } while (0)
; __device__ __forceinline__ void scan_phase(LAS unsigned char* lds, bf16* proj, int G, int bid) {
;     ...
;     for (int chain = bid; chain < 256; chain += G) {
;         const int b = chain >> 4, h = (chain >> 1) & 7, dir = chain & 1;
;         const int kcol = 1024 + dir * 1024 + h * 128;
;         f32x4 S[8];
; #pragma unroll
;         for (int i = 0; i < 8; ++i) S[i] = (f32x4){0.f, 0.f, 0.f, 0.f};
;         u32x4 rk = (u32x4){0u, 0u, 0u, 0u}, rq = rk, rv = rk;
;     ...
;         __syncthreads();
;         {
;             const u32x4 z4 = (u32x4){0u, 0u, 0u, 0u};
;             for (int o_ = tid * 16; o_ < 8192; o_ += NTHR * 16) { *(LAS u32x4*)(lds + O_KD + o_) = z4; *(LAS u32x4*)(lds + SET + O_KD + o_) = z4; *(LAS u32x4*)(lds + O_VT + o_) = z4; *(LAS u32x4*)(lds + O_VT + 8192 + o_) = z4; *(LAS u32x4*)(lds + O_VT + 16384 + o_) = z4; }
;         }
;         if (stager) SC_LOAD(0);
;         __syncthreads();
;         if (stager) { SC_WRITE(0); SC_LOAD(1); }
;         __syncthreads();
;         SC_PREP(0);
;         if (stager) { SC_WRITE(1); SC_LOAD(2); }
.LBB0_425:
	s_or_b64 exec, exec, s[4:5]
	s_waitcnt lgkmcnt(0)
	s_barrier
	ds_read2_b32 v[18:19], v81 offset1:132
	v_add_u32_e32 v0, 0x2000, v81
	ds_read2_b32 v[20:21], v0 offset0:64 offset1:196
	v_add_u32_e32 v0, 0x400, v81
	ds_read2_b32 v[22:23], v0 offset0:8 offset1:140
	v_add_u32_e32 v0, 0x2400, v81
	ds_read2_b32 v[24:25], v0 offset0:72 offset1:204
	s_waitcnt lgkmcnt(3)
	v_sub_f32_e32 v0, 1.0, v18
	v_max_f32_e32 v1, 0x3bdb8bac, v0
	v_sub_f32_e32 v0, 1.0, v19
	v_max_f32_e32 v0, 0x3bdb8bac, v0
	v_mul_f32_e32 v3, v1, v0
	s_waitcnt lgkmcnt(1)
	v_sub_f32_e32 v0, 1.0, v22
	v_max_f32_e32 v0, 0x3bdb8bac, v0
	v_mul_f32_e32 v17, v3, v0
	v_sub_f32_e32 v0, 1.0, v23
	v_max_f32_e32 v0, 0x3bdb8bac, v0
	v_mul_f32_e32 v28, v17, v0
	s_nop 1
	v_mul_f32_dpp v0, v28, v28 quad_perm:[0,0,1,2] row_mask:0xf bank_mask:0xf bound_ctrl:1
	v_cndmask_b32_e64 v0, v0, v28, s[44:45]
	s_nop 1
	v_mul_f32_dpp v26, v0, v0 quad_perm:[0,0,0,1] row_mask:0xf bank_mask:0xf bound_ctrl:1
	v_cndmask_b32_e64 v26, v0, v26, s[46:47]
	v_mov_b32_e32 v0, v2
	s_nop 1
	v_mov_b32_dpp v0, v26 quad_perm:[0,0,1,2] row_mask:0xf bank_mask:0xf
	v_cndmask_b32_e64 v29, v0, 1.0, s[44:45]
	v_mov_b32_e32 v0, v2
	v_mul_f32_e32 v1, v1, v29
	s_nop 0
	v_mov_b32_dpp v0, v26 quad_perm:[3,3,3,3] row_mask:0xf bank_mask:0xf
	v_rcp_f32_e32 v26, v1
	v_mul_f32_e32 v1, v20, v1
	v_cvt_pk_bf16_f32 v1, v1, s0
	ds_write_b16 v82, v1 offset:16896
	v_mul_f32_e32 v1, v3, v29
	v_rcp_f32_e32 v27, v1
	v_mul_f32_e32 v1, v21, v1
	v_cvt_pk_bf16_f32 v1, v1, s0
	ds_write_b16 v82, v1 offset:17168
	v_mul_f32_e32 v1, v17, v29
	v_rcp_f32_e32 v20, v1
	s_waitcnt lgkmcnt(2)
	v_mul_f32_e32 v1, v24, v1
	v_cvt_pk_bf16_f32 v1, v1, s0
	ds_write_b16 v82, v1 offset:17440
	v_mul_f32_e32 v1, v28, v29
	v_rcp_f32_e32 v21, v1
	v_mul_f32_e32 v1, v25, v1
	v_cvt_pk_bf16_f32 v1, v1, s0
	v_pk_mul_f32 v[18:19], v[18:19], v[26:27]
	ds_write_b16 v82, v1 offset:17712
	v_cvt_pk_bf16_f32 v1, v18, s0
	ds_write_b16 v82, v1 offset:21248
	v_pk_mul_f32 v[24:25], v[18:19], v[0:1] op_sel_hi:[1,0]
	v_cvt_pk_bf16_f32 v1, v19, s0
	v_pk_mul_f32 v[20:21], v[22:23], v[20:21]
	ds_write_b16 v82, v1 offset:21520
	v_cvt_pk_bf16_f32 v1, v20, s0
	ds_write_b16 v82, v1 offset:21792
	v_pk_mul_f32 v[22:23], v[20:21], v[0:1] op_sel_hi:[1,0]
	v_cvt_pk_bf16_f32 v1, v21, s0
	v_cvt_pk_bf16_f32 v18, v24, v25
	ds_write_b16 v82, v1 offset:22064
	v_cvt_pk_bf16_f32 v19, v22, v23
	v_add_u32_e32 v1, v54, v55
	ds_write_b64 v1, v[18:19] offset:25600
	s_and_saveexec_b64 s[4:5], s[44:45]
	v_readlane_b32 s74, v254, 33
	v_readlane_b32 s75, v254, 34
	v_add_u32_e32 v1, v54, v84
	ds_write_b32 v1, v0 offset:33792
	s_or_b64 exec, exec, s[4:5]
	s_add_i32 s16, s1, s0
	s_add_i32 s4, s16, 0x400
	s_mov_b32 s1, s72
	s_mov_b32 s5, s72
	v_mov_b64_e32 v[18:19], s[4:5]
	v_mov_b64_e32 v[0:1], s[0:1]
	s_and_saveexec_b64 s[18:19], s[40:41]
	s_xor_b64 s[34:35], exec, s[18:19]
	s_lshl_b32 s6, s14, 8
	s_add_i32 s17, s6, 0x10000
	s_sub_u32 s6, 0, s0
	s_subb_u32 s7, 0, 0
	v_mov_b64_e32 v[18:19], s[4:5]
	v_mov_b64_e32 v[0:1], s[0:1]
	s_or_saveexec_b64 s[4:5], s[34:35]
	v_mov_b64_e32 v[62:63], s[6:7]
	v_mov_b32_e32 v94, s17
	s_xor_b64 exec, exec, s[4:5]
	s_cbranch_execz .LBB0_431
	s_cmp_eq_u32 s15, 0
	s_cselect_b64 vcc, -1, 0
	s_lshl_b32 s1, s14, 8
	s_waitcnt vmcnt(1)
	v_lshlrev_b32_e32 v20, 16, v12
	v_and_b32_e32 v21, 0xffff0000, v12
	v_lshlrev_b32_e32 v24, 16, v4
	v_and_b32_e32 v25, 0xffff0000, v4
	v_lshlrev_b32_e32 v22, 16, v13
	v_and_b32_e32 v23, 0xffff0000, v13
	v_lshlrev_b32_e32 v26, 16, v5
	v_and_b32_e32 v27, 0xffff0000, v5
	v_lshlrev_b32_e32 v12, 16, v14
	v_and_b32_e32 v13, 0xffff0000, v14
	v_lshlrev_b32_e32 v4, 16, v6
	v_and_b32_e32 v5, 0xffff0000, v6
	v_lshlrev_b32_e32 v14, 16, v15
	v_and_b32_e32 v15, 0xffff0000, v15
	v_lshlrev_b32_e32 v6, 16, v7
	v_and_b32_e32 v7, 0xffff0000, v7
	s_add_i32 s18, s1, 0x10000
	v_cndmask_b32_e32 v1, v87, v86, vcc
	s_waitcnt vmcnt(0)
	ds_write_b16 v85, v8
	ds_write_b16_d16_hi v181, v8 offset:64
	ds_write_b128 v76, v[20:23] offset:34304
	ds_write_b128 v76, v[24:27] offset:42752
	ds_write_b16 v85, v9 offset:128
	ds_write_b16_d16_hi v181, v9 offset:192
	ds_write_b16 v85, v10 offset:256
	ds_write_b16_d16_hi v181, v10 offset:320
	ds_write_b128 v76, v[12:15] offset:34320
	ds_write_b128 v76, v[4:7] offset:42768
	ds_write_b16 v85, v11 offset:384
	ds_write_b16_d16_hi v181, v11 offset:448
	v_add_u32_e32 v1, s18, v1
	v_mov_b64_e32 v[4:5], s[82:83]
	v_mad_i64_i32 v[4:5], s[6:7], v1, s3, v[4:5]
	s_lshl_b32 s6, s0, 1
	s_mov_b32 s7, s72
	v_lshl_add_u64 v[4:5], v[4:5], 0, s[6:7]
	v_mov_b32_e32 v17, v2
	v_lshl_add_u64 v[8:9], v[4:5], 0, v[16:17]
	s_lshl_b32 s16, s16, 1
	s_mov_b32 s17, s72
	v_lshl_add_u64 v[10:11], v[8:9], 0, s[16:17]
	v_subrev_co_u32_e32 v10, vcc, s6, v10
	global_load_dwordx4 v[4:7], v[8:9], off
	s_nop 0
	v_subbrev_co_u32_e32 v11, vcc, 0, v11, vcc
	global_load_dwordx4 v[12:15], v[10:11], off offset:2048
	v_add_co_u32_e32 v8, vcc, 0x1000, v8
	s_sub_u32 s0, 0, s0
	s_nop 0
	v_addc_co_u32_e32 v9, vcc, 0, v9, vcc
	global_load_dwordx4 v[8:11], v[8:9], off offset:2048
	s_subb_u32 s1, 0, 0
	v_mov_b64_e32 v[62:63], s[0:1]
	v_mov_b32_e32 v94, s18
	s_cmp_eq_u32 s15, 0
	s_cselect_b64 vcc, -1, 0
	v_add_u32_e32 v168, 16, v86
	v_add_u32_e32 v169, -16, v87
	v_cndmask_b32_e32 v1, v169, v168, vcc
	v_add_u32_e32 v1, s18, v1
	v_mov_b64_e32 v[168:169], s[82:83]
	s_nop 0
	v_mad_i64_i32 v[168:169], vcc, v1, s3, v[168:169]
	v_lshl_add_u64 v[168:169], v[168:169], 0, s[6:7]
	v_lshl_add_u64 v[172:173], v[168:169], 0, v[16:17]
	v_lshl_add_u64 v[174:175], v[172:173], 0, s[16:17]
	v_subrev_co_u32_e32 v174, vcc, s6, v174
	s_nop 1
	v_subbrev_co_u32_e32 v175, vcc, 0, v175, vcc
	global_load_dwordx4 v[168:171], v[172:173], off
	global_load_dwordx4 v[176:179], v[174:175], off offset:2048
	v_add_co_u32_e32 v172, vcc, 0x1000, v172
	s_nop 1
	v_addc_co_u32_e32 v173, vcc, 0, v173, vcc
	global_load_dwordx4 v[172:175], v[172:173], off offset:2048

; __device__ __forceinline__ void scan_phase(LAS unsigned char* lds, bf16* proj, int G, int bid) {
;     ...
;         for (int c = 0; c < 272; ++c) {
;             LAS unsigned char* set = lds + (c & 1) * SET;
;             SC_PREP(c + 1);
;             {
;                 const LAS unsigned char* qeb = set + O_QE + fr * QST; const LAS unsigned char* keb = set + O_KE + fr * QST;
;                 bf16x8 kaf[4], qbf[4];
; #pragma unroll
;                 for (int i = 0; i < 4; ++i) { kaf[i] = *(const LAS bf16x8*)(keb + (32 * i + fq * 8) * 2); qbf[i] = *(const LAS bf16x8*)(qeb + (32 * i + fq * 8) * 2); }
;                 u32x2 qlo[4], qhi[4];
; #pragma unroll
;                 for (int i = 0; i < 4; ++i) { qlo[i] = *(const LAS u32x2*)(qeb + (32 * i + fq * 4) * 2); qhi[i] = *(const LAS u32x2*)(qeb + (32 * i + 16 + fq * 4) * 2); }
;                 const bf16x8 vf = *(const LAS bf16x8*)(lds + O_VT + (c % 3) * 8192 + (wave * 16 + fr) * 64 + fq * 16);
;                 f32x4 pt = (f32x4){0.f, 0.f, 0.f, 0.f};
;                 __builtin_amdgcn_s_setprio(1);
; #pragma unroll
;                 for (int i = 0; i < 4; ++i) pt = __builtin_amdgcn_mfma_f32_16x16x32_bf16(kaf[i], qbf[i], pt, 0, 0, 0);
;                 f32x4 oacc = (f32x4){0.f, 0.f, 0.f, 0.f};
; #pragma unroll
;                 for (int i = 0; i < 4; ++i) {
;                     u32x4 sw; sw.x = cvt_pk_bf16(S[2 * i][0], S[2 * i][1]); sw.y = cvt_pk_bf16(S[2 * i][2], S[2 * i][3]); sw.z = cvt_pk_bf16(S[2 * i + 1][0], S[2 * i + 1][1]); sw.w = cvt_pk_bf16(S[2 * i + 1][2], S[2 * i + 1][3]);
;                     u32x4 qw; qw.x = qlo[i][0]; qw.y = qlo[i][1]; qw.z = qhi[i][0]; qw.w = qhi[i][1];
;                     oacc = __builtin_amdgcn_mfma_f32_16x16x32_bf16(__builtin_bit_cast(bf16x8, sw), __builtin_bit_cast(bf16x8, qw), oacc, 0, 0, 0);
;                 }
;                 const LAS float* dv = (const LAS float*)(set + O_DV);
; #pragma unroll
;                 for (int kt = 0; kt < 8; ++kt) {
;                     const f32x4 d4 = *(const LAS f32x4*)(dv + kt * 16 + fq * 4);
;                     const bf16x8 ka = *(const LAS bf16x8*)(set + O_KD + (kt * 16 + fr) * 64 + fq * 16);
;                     S[kt] = __builtin_amdgcn_mfma_f32_16x16x32_bf16(ka, vf, S[kt] * d4, 0, 0, 0);
;                 }
; #pragma unroll
;                 for (int j = 0; j < 4; ++j) pt[j] = (fq * 4 + j <= fr) ? pt[j] : 0.f;
.LBB0_432:
	s_or_b64 exec, exec, s[0:1]
	s_waitcnt lgkmcnt(0)
	s_barrier
	s_add_i32 s4, s4, 16
	v_add_u32_e32 v97, -16, v97
	v_add_u32_e32 v96, -16, v96
	v_add_u32_e32 v95, 0x2000, v95
	s_cmpk_eq_i32 s4, 0x1100
	s_mov_b32 s6, s7
	s_cbranch_scc1 .LBB0_417
	s_branch .LscanB_433

; #define SC_LOAD(c_) do { const bf16* rp_ = proj + (size_t)scan_row16(b, dir, (c_), st) * HIN + h * 128 + sc8 * 8; \
;         rq = *(const u32x4*)rp_; rk = *(const u32x4*)(rp_ + kcol - h * 128); rv = *(const u32x4*)(rp_ + 3072); } while (0)
; __device__ __forceinline__ void scan_phase(LAS unsigned char* lds, bf16* proj, int G, int bid) {
;     ...
;                     *(u32x2*)(proj + (size_t)scan_row16(b, dir, c, fr) * HIN + kcol + wave * 16 + fq * 4) = ow;
;                 }
;             }
;             if (stager) { if (c + 2 < 272) SC_WRITE(c + 2); if (c + 3 < 272) SC_LOAD(c + 3); }
.LBB0_439:
	s_nop 0
	v_cvt_pk_bf16_f32 v48, v48, v49
	v_cvt_pk_bf16_f32 v49, v50, v51
	v_mad_i64_i32 v[0:1], s[0:1], v0, s3, v[66:67]
	global_store_dwordx2 v[0:1], v[48:49], off
	s_and_saveexec_b64 s[0:1], s[38:39]
	s_cbranch_execz .LBB0_432
	s_cmpk_gt_u32 s6, 0x10d
	s_cbranch_scc1 .LBB0_442
	v_lshlrev_b32_e32 v0, 2, v52
	v_add3_u32 v0, s14, v75, v0
	s_add_i32 s14, s6, 2
	s_and_b32 s15, s14, 0xffff
	s_mul_i32 s15, s15, 0xaaab
	s_lshr_b32 s15, s15, 17
	s_mul_i32 s15, s15, 3
	s_sub_i32 s14, s14, s15
	s_and_b32 s14, s14, 0xffff
	v_lshl_add_u32 v1, s14, 13, v77
	v_lshl_add_u32 v205, s14, 13, v180
	s_waitcnt vmcnt(4)
	v_lshlrev_b32_e32 v48, 16, v12
	v_and_b32_e32 v49, 0xffff0000, v12
	v_lshlrev_b32_e32 v98, 16, v4
	v_and_b32_e32 v99, 0xffff0000, v4
	v_lshlrev_b32_e32 v50, 16, v13
	v_and_b32_e32 v51, 0xffff0000, v13
	v_lshlrev_b32_e32 v100, 16, v5
	v_and_b32_e32 v101, 0xffff0000, v5
	ds_write_b16 v1, v8
	ds_write_b16_d16_hi v205, v8 offset:64
	ds_write_b128 v0, v[48:51]
	ds_write_b128 v0, v[98:101] offset:8448
	ds_write_b16 v1, v9 offset:128
	ds_write_b16_d16_hi v205, v9 offset:192
	v_lshlrev_b32_e32 v48, 16, v14
	v_and_b32_e32 v49, 0xffff0000, v14
	v_lshlrev_b32_e32 v98, 16, v6
	v_and_b32_e32 v99, 0xffff0000, v6
	v_lshlrev_b32_e32 v50, 16, v15
	v_and_b32_e32 v51, 0xffff0000, v15
	v_lshlrev_b32_e32 v100, 16, v7
	v_and_b32_e32 v101, 0xffff0000, v7
	ds_write_b16 v1, v10 offset:256
	ds_write_b16_d16_hi v205, v10 offset:320
	ds_write_b128 v0, v[48:51] offset:16
	ds_write_b128 v0, v[98:101] offset:8464
	ds_write_b16 v1, v11 offset:384
	ds_write_b16_d16_hi v205, v11 offset:448
.LBB0_442:
	s_cmpk_gt_u32 s6, 0x10b
	s_cbranch_scc1 .LBB0_432
	s_cmp_lt_u32 s6, 12
	s_cselect_b64 vcc, -1, 0
	s_and_b64 s[14:15], vcc, exec
	s_movk_i32 s14, 0xfff
	s_cselect_b32 s6, 64, 0xffffff40
	s_cselect_b32 s14, 0xff, s14
	s_add_i32 s15, s4, s6
	s_sub_i32 s6, s14, s6
	v_mov_b32_e32 v0, s5
	v_add_u32_e32 v1, s15, v70
	v_add_u32_e32 v3, s6, v97
	v_cndmask_b32_e32 v0, v0, v94, vcc
	v_cndmask_b32_e64 v1, v3, v1, s[56:57]
	v_add_u32_e32 v0, v1, v0
	v_mad_i64_i32 v[0:1], s[14:15], v0, s3, v[68:69]
	v_mov_b32_e32 v65, v2
	v_lshl_add_u64 v[4:5], v[0:1], 0, v[64:65]
	v_lshl_add_u64 v[8:9], v[62:63], 1, v[4:5]
	global_load_dwordx4 v[4:7], v[0:1], off
	global_load_dwordx4 v[12:15], v[8:9], off
	v_add_co_u32_e32 v0, vcc, 0x1000, v0
	s_nop 1
	v_addc_co_u32_e32 v1, vcc, 0, v1, vcc
	global_load_dwordx4 v[8:11], v[0:1], off offset:2048
	s_branch .LBB0_432

; #define SC_LOAD(c_) do { const bf16* rp_ = proj + (size_t)scan_row16(b, dir, (c_), st) * HIN + h * 128 + sc8 * 8; \
;         rq = *(const u32x4*)rp_; rk = *(const u32x4*)(rp_ + kcol - h * 128); rv = *(const u32x4*)(rp_ + 3072); } while (0)
; __device__ __forceinline__ void scan_phase(LAS unsigned char* lds, bf16* proj, int G, int bid) {
;     ...
;                     *(u32x2*)(proj + (size_t)scan_row16(b, dir, c, fr) * HIN + kcol + wave * 16 + fq * 4) = ow;
;                 }
;             }
;             if (stager) { if (c + 2 < 272) SC_WRITE(c + 2); if (c + 3 < 272) SC_LOAD(c + 3); }
.LscanB_439:
	s_nop 0
	v_cvt_pk_bf16_f32 v48, v48, v49
	v_cvt_pk_bf16_f32 v49, v50, v51
	v_mad_i64_i32 v[0:1], s[0:1], v0, s3, v[66:67]
	global_store_dwordx2 v[0:1], v[48:49], off
	s_and_saveexec_b64 s[0:1], s[38:39]
	s_cbranch_execz .LscanB_432
	s_cmpk_gt_u32 s6, 0x10d
	s_cbranch_scc1 .LscanB_442
	v_lshlrev_b32_e32 v0, 2, v52
	v_add3_u32 v0, s14, v75, v0
	s_add_i32 s14, s6, 2
	s_and_b32 s15, s14, 0xffff
	s_mul_i32 s15, s15, 0xaaab
	s_lshr_b32 s15, s15, 17
	s_mul_i32 s15, s15, 3
	s_sub_i32 s14, s14, s15
	s_and_b32 s14, s14, 0xffff
	v_lshl_add_u32 v1, s14, 13, v77
	v_lshl_add_u32 v205, s14, 13, v180
	s_cmpk_eq_u32 s6, 0x10d
	s_cbranch_scc1 .LscanB_wtail
	s_waitcnt vmcnt(4)
	s_branch .LscanB_wgo

; #define SC_LOAD(c_) do { const bf16* rp_ = proj + (size_t)scan_row16(b, dir, (c_), st) * HIN + h * 128 + sc8 * 8; \
;         rq = *(const u32x4*)rp_; rk = *(const u32x4*)(rp_ + kcol - h * 128); rv = *(const u32x4*)(rp_ + 3072); } while (0)
; __device__ __forceinline__ void scan_phase(LAS unsigned char* lds, bf16* proj, int G, int bid) {
;     ...
;             if (stager) { if (c + 2 < 272) SC_WRITE(c + 2); if (c + 3 < 272) SC_LOAD(c + 3); }
.LscanB_wgo:
	v_lshlrev_b32_e32 v48, 16, v176
	v_and_b32_e32 v49, 0xffff0000, v176
	v_lshlrev_b32_e32 v98, 16, v168
	v_and_b32_e32 v99, 0xffff0000, v168
	v_lshlrev_b32_e32 v50, 16, v177
	v_and_b32_e32 v51, 0xffff0000, v177
	v_lshlrev_b32_e32 v100, 16, v169
	v_and_b32_e32 v101, 0xffff0000, v169
	ds_write_b16 v1, v172
	ds_write_b16_d16_hi v205, v172 offset:64
	ds_write_b128 v0, v[48:51]
	ds_write_b128 v0, v[98:101] offset:8448
	ds_write_b16 v1, v173 offset:128
	ds_write_b16_d16_hi v205, v173 offset:192
	v_lshlrev_b32_e32 v48, 16, v178
	v_and_b32_e32 v49, 0xffff0000, v178
	v_lshlrev_b32_e32 v98, 16, v170
	v_and_b32_e32 v99, 0xffff0000, v170
	v_lshlrev_b32_e32 v50, 16, v179
	v_and_b32_e32 v51, 0xffff0000, v179
	v_lshlrev_b32_e32 v100, 16, v171
	v_and_b32_e32 v101, 0xffff0000, v171
	ds_write_b16 v1, v174 offset:256
	ds_write_b16_d16_hi v205, v174 offset:320
	ds_write_b128 v0, v[48:51] offset:16
	ds_write_b128 v0, v[98:101] offset:8464
	ds_write_b16 v1, v175 offset:384
	ds_write_b16_d16_hi v205, v175 offset:448
.LscanB_442:
	s_cmpk_gt_u32 s6, 0x10b
	s_cbranch_scc1 .LscanB_432
	s_cmp_lt_u32 s6, 12
	s_cselect_b64 vcc, -1, 0
	s_and_b64 s[14:15], vcc, exec
	s_movk_i32 s14, 0xfff
	s_cselect_b32 s6, 64, 0xffffff40
	s_cselect_b32 s14, 0xff, s14
	s_add_i32 s15, s4, s6
	s_sub_i32 s6, s14, s6
	v_mov_b32_e32 v0, s5
	v_add_u32_e32 v1, s15, v70
	v_add_u32_e32 v3, s6, v97
	v_cndmask_b32_e32 v0, v0, v94, vcc
	v_cndmask_b32_e64 v1, v3, v1, s[56:57]
	v_add_u32_e32 v0, v1, v0
	v_mad_i64_i32 v[0:1], s[14:15], v0, s3, v[68:69]
	v_mov_b32_e32 v65, v2
	v_lshl_add_u64 v[168:169], v[0:1], 0, v[64:65]
	v_lshl_add_u64 v[172:173], v[62:63], 1, v[168:169]
	global_load_dwordx4 v[168:171], v[0:1], off
	global_load_dwordx4 v[176:179], v[172:173], off
	v_add_co_u32_e32 v0, vcc, 0x1000, v0
	s_nop 1
	v_addc_co_u32_e32 v1, vcc, 0, v1, vcc
	global_load_dwordx4 v[172:175], v[0:1], off offset:2048
	s_branch .LscanB_432
